# layer-0 weight-copy split: 1792 tiles in the prologue, 11 per idle workgroup in G1(0)'s tail (was 1536 / 13); on top of tail pulls 3/2
# baseline (speedup 1.0000x reference)
.LBB0_84:
	s_or_b64 exec, exec, s[2:3]
	s_add_i32 s46, 0, 0x20180
	v_mov_b32_e32 v1, s46
	s_waitcnt lgkmcnt(0)
	s_barrier
	ds_read_b32 v1, v1
	s_mov_b32 s21, 0
	s_waitcnt lgkmcnt(0)
	v_readfirstlane_b32 s47, v1
	s_cmpk_gt_i32 s47, 0x6ff
	s_cbranch_scc1 .LBB0_147
	s_ashr_i32 s2, s22, 6
	v_bfe_u32 v3, v2, 5, 1
	v_and_b32_e32 v4, 31, v2
	v_lshlrev_b32_e32 v1, 1, v3
	s_lshl_b32 s3, s2, 3
	v_lshlrev_b32_e32 v3, 2, v3
	v_lshlrev_b32_e32 v54, 2, v4
	v_lshlrev_b32_e32 v55, 10, v4
	v_lshlrev_b32_e32 v4, 3, v4
	v_or_b32_e32 v5, s3, v3
	v_bitop3_b32 v57, s3, v4, v3 bitop3:0x36
	v_add_u32_e32 v3, 64, v5
	v_xor_b32_e32 v58, v3, v4
	v_add_u32_e32 v3, 0x80, v5
	v_xor_b32_e32 v59, v3, v4
	v_add_u32_e32 v3, 0xc0, v5
	v_lshl_or_b32 v1, s2, 2, v1
	s_lshl_b32 s4, s2, 4
	v_lshlrev_b32_e32 v7, 4, v2
	v_xor_b32_e32 v60, v3, v4
	s_lshl_b32 s2, s2, 5
	v_mov_b32_e32 v3, 0xf0
	v_bfe_u32 v6, v2, 4, 2
	v_bitop3_b32 v62, s2, v3, v7 bitop3:0x48
	s_or_b32 s2, s4, 8
	v_or_b32_e32 v4, s2, v6
	s_lshl_b32 s2, s2, 1
	v_bitop3_b32 v64, s2, v3, v7 bitop3:0x48
	s_or_b32 s2, s4, 12
	v_readlane_b32 s80, v250, 5
	v_lshlrev_b32_e32 v63, 8, v4
	v_or_b32_e32 v4, s2, v6
	s_lshl_b32 s2, s2, 1
	v_readlane_b32 s94, v250, 19
	v_readlane_b32 s95, v250, 20
	s_add_u32 s22, s94, 0x14400000
	s_addc_u32 s23, s95, 0
	s_add_u32 s24, s94, 0x9400000
	v_lshlrev_b32_e32 v2, 3, v2
	s_addc_u32 s25, s95, 0
	v_or_b32_e32 v56, s4, v6
	v_and_b32_e32 v2, 0x78, v2
	s_add_u32 s26, s94, 0x7400000
	v_mov_b32_e32 v51, 0
	v_lshlrev_b32_e32 v61, 8, v56
	v_lshlrev_b32_e32 v65, 8, v4
	v_bitop3_b32 v66, s2, v3, v7 bitop3:0x48
	s_addc_u32 s27, s95, 0
	v_lshlrev_b32_e32 v50, 1, v2
	v_mov_b32_e32 v67, 0x80
	v_mov_b32_e32 v68, 10
	v_mov_b32_e32 v69, 5
	v_mov_b32_e32 v70, 7
	s_mov_b32 s48, 0
	v_readlane_b32 s81, v250, 6
	v_readlane_b32 s82, v250, 7
	v_readlane_b32 s83, v250, 8
	v_readlane_b32 s84, v250, 9
	v_readlane_b32 s85, v250, 10
	v_readlane_b32 s86, v250, 11
	v_readlane_b32 s87, v250, 12
	v_readlane_b32 s88, v250, 13
	v_readlane_b32 s89, v250, 14
	v_readlane_b32 s90, v250, 15
	v_readlane_b32 s91, v250, 16
	v_readlane_b32 s92, v250, 17
	v_readlane_b32 s93, v250, 18
	s_branch .LBB0_87
.LBB0_86:
	s_or_b64 exec, exec, s[2:3]
	s_waitcnt vmcnt(0)
	v_mov_b32_e32 v2, s46
	s_waitcnt lgkmcnt(0)
	s_barrier
	ds_read_b32 v2, v2
	s_waitcnt lgkmcnt(0)
	v_readfirstlane_b32 s47, v2
	s_cmpk_lt_i32 s47, 0x700
	s_cbranch_scc0 .LBB0_147

.LBB0_91:
	s_or_b64 exec, exec, s[2:3]
	s_sub_i32 s2, 0x700, s47
	s_min_i32 s49, s2, 4
	s_max_i32 s2, s49, 1
	v_mov_b32_e32 v2, 0
	s_mov_b32 s50, 1
	s_lshl_b32 s51, s2, 3
	s_lshl_b32 s52, s47, 7
	s_lshl_b32 s53, s47, 3
	s_mov_b64 s[30:31], 0
	s_mov_b32 s54, 0
	v_mov_b32_e32 v3, v2
	v_mov_b32_e32 v4, v2
	v_mov_b32_e32 v5, v2
	v_mov_b32_e32 v10, v2
	v_mov_b32_e32 v11, v2
	v_mov_b32_e32 v12, v2
	v_mov_b32_e32 v13, v2
	v_mov_b32_e32 v18, v2
	v_mov_b32_e32 v19, v2
	v_mov_b32_e32 v20, v2
	v_mov_b32_e32 v21, v2
	v_mov_b32_e32 v26, v2
	v_mov_b32_e32 v27, v2
	v_mov_b32_e32 v28, v2
	v_mov_b32_e32 v29, v2
	v_mov_b32_e32 v6, v2
	v_mov_b32_e32 v7, v2
	v_mov_b32_e32 v8, v2
	v_mov_b32_e32 v9, v2
	v_mov_b32_e32 v14, v2
	v_mov_b32_e32 v15, v2
	v_mov_b32_e32 v16, v2
	v_mov_b32_e32 v17, v2
	v_mov_b32_e32 v22, v2
	v_mov_b32_e32 v23, v2
	v_mov_b32_e32 v24, v2
	v_mov_b32_e32 v25, v2
	v_mov_b32_e32 v30, v2
	v_mov_b32_e32 v31, v2
	v_mov_b32_e32 v32, v2
	v_mov_b32_e32 v33, v2
	s_branch .LBB0_93

.LBB0_406:
	v_readlane_b32 s0, v255, 2
	s_cmp_eq_u32 s0, 3
	v_readlane_b32 s1, v255, 3
	s_cbranch_scc1 .LBB0_469
	v_readlane_b32 s0, v253, 48
	v_readlane_b32 s1, v253, 49
	s_andn2_b64 vcc, exec, s[0:1]
	s_cbranch_vccnz .LBB0_469
	v_readlane_b32 s0, v255, 2
	v_readlane_b32 s8, v250, 5
	v_readlane_b32 s1, v255, 3
	v_mov_b32_e32 v2, v0
	v_readlane_b32 s9, v250, 6
	v_readlane_b32 s10, v250, 7
	v_readlane_b32 s11, v250, 8
	v_readlane_b32 s14, v250, 11
	v_readlane_b32 s15, v250, 12
	v_readlane_b32 s16, v250, 13
	v_readlane_b32 s17, v250, 14
	v_readlane_b32 s18, v250, 15
	v_readlane_b32 s19, v250, 16
	s_add_i32 s0, s0, 1
	s_cmp_eq_u32 s0, 1
	s_cselect_b32 s0, 0, s0
	v_readlane_b32 s12, v250, 9
	v_readfirstlane_b32 s1, v2
	v_readlane_b32 s13, v250, 10
	s_mov_b64 s[10:11], s[14:15]
	s_mov_b64 s[4:5], s[18:19]
	s_mov_b64 s[2:3], s[62:63]
	s_mov_b64 s[8:9], s[16:17]
	v_cmp_eq_u32_e32 vcc, 0, v2
	v_readlane_b32 s20, v250, 17
	v_readlane_b32 s21, v250, 18
	v_readlane_b32 s22, v250, 19
	v_readlane_b32 s23, v250, 20
	s_waitcnt vmcnt(0)
	s_barrier
	s_and_saveexec_b64 s[12:13], vcc
	s_cbranch_execz .LBB0_412
	s_mov_b64 s[16:17], exec
	v_mbcnt_lo_u32_b32 v3, s16, 0
	v_mbcnt_hi_u32_b32 v3, s17, v3
	v_cmp_eq_u32_e32 vcc, 0, v3
	s_and_saveexec_b64 s[14:15], vcc
	s_cbranch_execz .LBB0_411
	s_lshl_b32 s28, s0, 6
	s_lshl_b64 s[18:19], s[28:29], 2
	v_readlane_b32 s20, v252, 11
	s_add_u32 s18, s20, s18
	v_readlane_b32 s20, v252, 12
	s_addc_u32 s19, s20, s19
	v_readlane_b32 s20, v255, 2
	s_cmp_eq_u32 s20, 0
	s_cselect_b32 s20, 0x80, 0
	s_add_u32 s18, s18, s20
	s_addc_u32 s19, s19, 0
	s_bcnt1_i32_b64 s16, s[16:17]
	v_readlane_b32 s20, v255, 2
	s_cmp_eq_u32 s20, 0
	s_cselect_b32 s20, 11, 3
	s_mul_i32 s16, s16, s20
	s_waitcnt lgkmcnt(1)
	v_mov_b32_e32 v4, s16
	global_atomic_add v4, v67, v4, s[18:19] sc0

.LBB0_412:
	s_or_b64 exec, exec, s[12:13]
	v_readlane_b32 s12, v254, 19
	s_waitcnt lgkmcnt(0)
	s_barrier
	v_mov_b32_e32 v3, s12
	ds_read_b32 v3, v3
	s_waitcnt lgkmcnt(0)
	v_readfirstlane_b32 s25, v3
	v_readlane_b32 s12, v255, 2
	s_cmp_eq_u32 s12, 0
	s_cselect_b32 s12, 0x700, 0
	s_add_i32 s25, s25, s12
	s_cmpk_gt_i32 s25, 0xc3f
	s_cbranch_scc1 .LBB0_468
	s_ashr_i32 s14, s1, 6
	s_mul_i32 s16, s0, 0x2c00000
	s_mul_hi_u32 s17, s0, 0x2c00000
	s_add_u32 s4, s4, s16
	s_addc_u32 s5, s5, s17
	s_mul_i32 s13, s0, 0x5800000
	s_mov_b32 s1, s29
	s_mul_hi_u32 s12, s0, 0x5800000
	s_add_u32 s8, s8, s13
	s_addc_u32 s9, s9, s12
	s_lshl_b64 s[12:13], s[0:1], 24
	s_add_u32 s10, s10, s12
	s_addc_u32 s11, s11, s13
	s_mul_i32 s12, s0, 0x3000000
	v_bfe_u32 v3, v2, 5, 1
	s_mul_hi_u32 s13, s0, 0x3000000
	s_add_u32 s12, s2, s12
	s_addc_u32 s13, s3, s13
	v_lshlrev_b32_e32 v5, 1, v3
	s_lshl_b32 s2, s14, 3
	v_lshlrev_b32_e32 v3, 2, v3
	v_and_b32_e32 v4, 31, v2
	v_or_b32_e32 v6, s2, v3
	v_bfe_u32 v7, v2, 4, 2
	v_lshlrev_b32_e32 v8, 4, v2
	v_lshlrev_b32_e32 v2, 3, v2
	v_lshl_or_b32 v52, s14, 2, v5
	v_lshlrev_b32_e32 v53, 2, v4
	v_lshlrev_b32_e32 v54, 10, v4
	v_lshlrev_b32_e32 v5, 3, v4
	v_and_b32_e32 v4, 0x78, v2
	v_add_u32_e32 v2, 64, v6
	s_lshl_b32 s3, s14, 4
	v_bitop3_b32 v56, s2, v5, v3 bitop3:0x36
	v_xor_b32_e32 v57, v2, v5
	v_add_u32_e32 v2, 0x80, v6
	s_lshl_b32 s2, s14, 5
	v_mov_b32_e32 v3, 0xf0
	v_xor_b32_e32 v58, v2, v5
	v_add_u32_e32 v2, 0xc0, v6
	v_bitop3_b32 v61, s2, v3, v8 bitop3:0x48
	s_or_b32 s2, s3, 8
	v_xor_b32_e32 v59, v2, v5
	v_or_b32_e32 v2, s2, v7
	s_lshl_b32 s2, s2, 1
	s_sub_i32 s18, 0xc40, s25
	v_bitop3_b32 v63, s2, v3, v8 bitop3:0x48
	s_or_b32 s2, s3, 12
	v_readlane_b32 s51, v255, 2
	s_cmp_eq_u32 s51, 0
	s_cselect_b32 s51, 11, 3
	s_min_i32 s51, s18, s51
	v_lshlrev_b32_e32 v62, 8, v2
	v_or_b32_e32 v2, s2, v7
	s_lshl_b32 s2, s2, 1
	s_mul_i32 s14, s0, 0x1600000
	s_max_i32 s22, s51, 1
	v_readlane_b32 s18, v252, 13
	s_mul_hi_u32 s15, s0, 0x1600000
	s_add_u32 s14, s18, s14
	v_readlane_b32 s18, v252, 14
	s_addc_u32 s15, s18, s15
	v_readlane_b32 s18, v252, 15
	s_add_u32 s16, s18, s16
	v_readlane_b32 s18, v252, 16
	v_or_b32_e32 v55, s3, v7
	v_bitop3_b32 v65, s2, v3, v8 bitop3:0x48
	s_mul_hi_u32 s2, s0, 0x1b00000
	s_mul_i32 s3, s0, 0x1b00000
	s_addc_u32 s17, s18, s17
	s_lshl_b64 s[0:1], s[0:1], 23
	v_readlane_b32 s18, v252, 17
	s_add_u32 s18, s18, s0
	v_readlane_b32 s0, v252, 18
	s_addc_u32 s19, s0, s1
	v_readlane_b32 s0, v252, 1
	v_lshlrev_b32_e32 v64, 8, v2
	s_add_u32 s20, s0, s3
	v_readlane_b32 s0, v252, 2
	v_mov_b32_e32 v2, 0
	s_mov_b32 s50, 1
	v_lshlrev_b32_e32 v60, 8, v55
	s_addc_u32 s21, s0, s2
	s_lshl_b32 s52, s22, 3
	s_lshl_b32 s53, s25, 7
	s_lshl_b32 s54, s25, 3
	s_mov_b64 s[22:23], 0
	s_mov_b32 s55, 0
	v_lshlrev_b32_e32 v66, 1, v4
	s_mov_b32 s56, 0
	v_mov_b32_e32 v3, v2
	v_mov_b32_e32 v4, v2
	v_mov_b32_e32 v5, v2
	v_mov_b32_e32 v10, v2
	v_mov_b32_e32 v11, v2
	v_mov_b32_e32 v12, v2
	v_mov_b32_e32 v13, v2
	v_mov_b32_e32 v18, v2
	v_mov_b32_e32 v19, v2
	v_mov_b32_e32 v20, v2
	v_mov_b32_e32 v21, v2
	v_mov_b32_e32 v26, v2
	v_mov_b32_e32 v27, v2
	v_mov_b32_e32 v28, v2
	v_mov_b32_e32 v29, v2
	v_mov_b32_e32 v6, v2
	v_mov_b32_e32 v7, v2
	v_mov_b32_e32 v8, v2
	v_mov_b32_e32 v9, v2
	v_mov_b32_e32 v14, v2
	v_mov_b32_e32 v15, v2
	v_mov_b32_e32 v16, v2
	v_mov_b32_e32 v17, v2
	v_mov_b32_e32 v22, v2
	v_mov_b32_e32 v23, v2
	v_mov_b32_e32 v24, v2
	v_mov_b32_e32 v25, v2
	v_mov_b32_e32 v30, v2
	v_mov_b32_e32 v31, v2
	v_mov_b32_e32 v32, v2
	v_mov_b32_e32 v33, v2
	s_branch .LBB0_415
